# retention scan: the 4-step score chain's LDS reads issued ahead with counted lgkmcnt waits (was read-wait-MFMA serialized four times)
# speedup vs baseline: 1.0177x; 1.0071x over previous
; __device__ __forceinline__ unsigned pk2(float lo, float hi) { f32x2_t v = {lo, hi}; bf16x2_t b = __builtin_convertvector(v, bf16x2_t); return __builtin_bit_cast(unsigned, b); }
; template <int MODE>
; __device__ void scan_unit(int swave, const Params& p, int j, int b, int h, int dir, char* shm) {
;     ...
;       const int c6 = vg * 6;
;       vT[(c6 + 0) * VS + ti] = (bf16_t)(R.v30 & 0xffff); vT[(c6 + 1) * VS + ti] = (bf16_t)(R.v30 >> 16);
;       vT[(c6 + 2) * VS + ti] = (bf16_t)(R.v31 & 0xffff); vT[(c6 + 3) * VS + ti] = (bf16_t)(R.v31 >> 16);
;       vT[(c6 + 4) * VS + ti] = (bf16_t)(R.v32 & 0xffff); vT[(c6 + 5) * VS + ti] = (bf16_t)(R.v32 >> 16);
;     }
;   };
;   f32x4 S[4][NVT];
; #pragma unroll
;   for (int a = 0; a < 4; ++a)
; #pragma unroll
;     for (int t = 0; t < NVT; ++t) S[a][t] = (f32x4){0.f, 0.f, 0.f, 0.f};
;   auto compute = [&](const char* buf, bf16_t* obuf) {
;     const bf16_t* qin = (const bf16_t*)buf; const bf16_t* ktil = (const bf16_t*)(buf + OFF_KT); const bf16_t* koutT = (const bf16_t*)(buf + OFF_KO);
;     const bf16_t* vT = (const bf16_t*)(buf + OFF_VT); const float* dec = (const float*)(buf + OFF_DEC);
;     bf16x8 Asc = {0, 0, 0, 0, 0, 0, 0, 0};
;     if (KS == 1 || wk == 0) {
;       f32x4 sc = {0.f, 0.f, 0.f, 0.f};
; #pragma unroll
;       for (int m = 0; m < DK / 32; ++m) {
;         const bf16x8 a = *(const bf16x8*)(ktil + r * QS + m * 32 + q4 * 8);
;         const bf16x8 bb = *(const bf16x8*)(qin + r * QS + m * 32 + q4 * 8);
;         sc = __builtin_amdgcn_mfma_f32_16x16x32_bf16(a, bb, sc, 0, 0, 0);
;       }
;       {
;         const unsigned p01 = pk2(q4 * 4 + 0 > r ? 0.f : sc[0], q4 * 4 + 1 > r ? 0.f : sc[1]);
;         const unsigned p23 = pk2(q4 * 4 + 2 > r ? 0.f : sc[2], q4 * 4 + 3 > r ? 0.f : sc[3]);
;         Asc[0] = (short)(p01 & 0xffff); Asc[1] = (short)(p01 >> 16); Asc[2] = (short)(p23 & 0xffff); Asc[3] = (short)(p23 >> 16);
;       }
.LBB0_580:
	s_or_b64 exec, exec, s[2:3]
	v_mov_b32_e32 v4, 0
	v_mov_b32_e32 v68, 0
	v_mov_b32_e32 v69, 0
	v_mov_b32_e32 v70, 0
	v_mov_b32_e32 v71, 0
	ds_write_b16 v159, v108
	ds_write_b16_d16_hi v230, v108
	ds_write_b16 v231, v0
	ds_write_b16_d16_hi v232, v0
	ds_write_b16 v233, v1
	ds_write_b16_d16_hi v234, v1
	s_and_saveexec_b64 s[2:3], s[6:7]
	s_cbranch_execz .LBB0_582
	ds_read_b128 v[6:9], v160 offset:4352
	ds_read_b128 v[68:71], v160
	ds_read_b128 v[76:79], v160 offset:4416
	ds_read_b128 v[80:83], v160 offset:64
	ds_read_b128 v[72:75], v160 offset:4480
	s_pack_ll_b32_b16 s20, 0, 0
	s_waitcnt lgkmcnt(3)
	v_mfma_f32_16x16x32_bf16 v[6:9], v[6:9], v[68:71], 0
	ds_read_b128 v[68:71], v160 offset:128
	s_waitcnt lgkmcnt(2)
	v_mfma_f32_16x16x32_bf16 v[6:9], v[76:79], v[80:83], v[6:9]
	ds_read_b128 v[76:79], v160 offset:4544
	ds_read_b128 v[80:83], v160 offset:192
	s_waitcnt lgkmcnt(2)
	v_mfma_f32_16x16x32_bf16 v[6:9], v[72:75], v[68:71], v[6:9]
	s_waitcnt lgkmcnt(0)
	v_mfma_f32_16x16x32_bf16 v[6:9], v[76:79], v[80:83], v[6:9]
	v_mov_b32_e32 v70, s20
	v_mov_b32_e32 v71, s20
	s_nop 5
	v_cndmask_b32_e64 v0, v6, 0, s[8:9]
	v_cndmask_b32_e64 v1, 0, v7, s[10:11]
	v_cvt_pk_bf16_f32 v68, v0, v1
	v_cndmask_b32_e64 v0, v8, 0, s[12:13]
	v_cndmask_b32_e64 v1, v9, 0, s[14:15]
	v_cvt_pk_bf16_f32 v69, v0, v1

; __device__ __forceinline__ bf16_t f2bf(float f) { return (bf16_t)(pk2(f, 0.f) & 0xffffu); }
; template <int MODE>
; __device__ void scan_unit(int swave, const Params& p, int j, int b, int h, int dir, char* shm) {
;     ...
;     if (KS == 1 || wk == 0) {
;       f32x4 sc = {0.f, 0.f, 0.f, 0.f};
; #pragma unroll
;       for (int m = 0; m < DK / 32; ++m) {
;         const bf16x8 a = *(const bf16x8*)(ktil + r * QS + m * 32 + q4 * 8);
;         const bf16x8 bb = *(const bf16x8*)(qin + r * QS + m * 32 + q4 * 8);
;         sc = __builtin_amdgcn_mfma_f32_16x16x32_bf16(a, bb, sc, 0, 0, 0);
;       }
;       {
;     ...
;     for (int m = 0; m < 2; ++m) {
;       const uint2 lo = *(const uint2*)(qin + r * QS + slab + (2 * m) * 16 + q4 * 4);
;       const uint2 hi = *(const uint2*)(qin + r * QS + slab + (2 * m + 1) * 16 + q4 * 4);
;       Aq[m] = (bf16x8){(short)(lo.x & 0xffff), (short)(lo.x >> 16), (short)(lo.y & 0xffff), (short)(lo.y >> 16),
;                        (short)(hi.x & 0xffff), (short)(hi.x >> 16), (short)(hi.y & 0xffff), (short)(hi.y >> 16)};
;     }
;     f32x4 o[NVT];
; #pragma unroll
;     for (int t = 0; t < NVT; ++t) {
;       o[t] = (f32x4){0.f, 0.f, 0.f, 0.f};
;       if (KS == 1 || wk == 0) o[t] = __builtin_amdgcn_mfma_f32_16x16x32_bf16(Asc, Bv[t], o[t], 0, 0, 0);
;     }
; #pragma unroll
;     for (int m = 0; m < 2; ++m)
; #pragma unroll
;       for (int t = 0; t < NVT; ++t) {
;         const f32x4 s0 = S[2 * m][t], s1 = S[2 * m + 1][t];
;         union { unsigned u[4]; bf16x8 v; } cv;
;         cv.u[0] = pk2(s0[0], s0[1]); cv.u[1] = pk2(s0[2], s0[3]); cv.u[2] = pk2(s1[0], s1[1]); cv.u[3] = pk2(s1[2], s1[3]);
;         o[t] = __builtin_amdgcn_mfma_f32_16x16x32_bf16(Aq[m], cv.v, o[t], 0, 0, 0);
;       }
; #pragma unroll
;     for (int t = 0; t < NVT; ++t)
; #pragma unroll
;       for (int jj = 0; jj < 4; ++jj) obuf[(wk * 16 + q4 * 4 + jj) * OS + (vt0 + t) * 16 + r] = f2bf(o[t][jj]);
; #pragma unroll
;     for (int kt = 0; kt < 4; ++kt) {
;       const uint2 kk = *(const uint2*)(koutT + (slab + kt * 16 + r) * 16 + q4 * 4);
;       const bf16x8 Ak = {(short)(kk.x & 0xffff), (short)(kk.x >> 16), (short)(kk.y & 0xffff), (short)(kk.y >> 16), 0, 0, 0, 0};
;       const f32x4 dc = *(const f32x4*)(dec + slab + kt * 16 + q4 * 4);
; #pragma unroll
;       for (int t = 0; t < NVT; ++t) S[kt][t] = __builtin_amdgcn_mfma_f32_16x16x32_bf16(Ak, Bv[t], S[kt][t] * dc, 0, 0, 0);
.LBB0_588:
	s_or_b64 exec, exec, s[2:3]
	s_waitcnt lgkmcnt(1)
	v_bfi_b32 v84, s30, v84, v84
	s_waitcnt lgkmcnt(0)
	v_bfi_b32 v10, s30, v10, v10
	v_cvt_pk_bf16_f32 v68, v24, v25
	v_cvt_pk_bf16_f32 v69, v26, v27
	v_cvt_pk_bf16_f32 v70, v64, v65
	v_cvt_pk_bf16_f32 v71, v66, v67
	v_mov_b32_e32 v81, 0
	s_nop 0
	v_mfma_f32_16x16x32_bf16 v[68:71], v[82:85], v[68:71], v[86:89]
	s_nop 2
	v_cvt_pk_bf16_f32 v86, v28, v29
	v_cvt_pk_bf16_f32 v87, v30, v31
	v_cvt_pk_bf16_f32 v88, v60, v61
	v_cvt_pk_bf16_f32 v89, v62, v63
	s_nop 1
	v_mfma_f32_16x16x32_bf16 v[4:7], v[82:85], v[86:89], v[4:7]
	v_cvt_pk_bf16_f32 v86, v40, v41
	v_cvt_pk_bf16_f32 v87, v42, v43
	v_cvt_pk_bf16_f32 v88, v56, v57
	v_cvt_pk_bf16_f32 v89, v58, v59
	s_nop 1
	v_mfma_f32_16x16x32_bf16 v[82:85], v[82:85], v[86:89], v[90:93]
	v_cvt_pk_bf16_f32 v86, v52, v53
	v_cvt_pk_bf16_f32 v87, v54, v55
	v_cvt_pk_bf16_f32 v88, v36, v37
	v_cvt_pk_bf16_f32 v89, v38, v39
	s_nop 1
	v_mfma_f32_16x16x32_bf16 v[68:71], v[8:11], v[86:89], v[68:71]
	v_cvt_pk_bf16_f32 v86, v48, v49
	v_cvt_pk_bf16_f32 v87, v50, v51
	v_cvt_pk_bf16_f32 v88, v32, v33
	v_cvt_pk_bf16_f32 v89, v34, v35
	s_nop 1
	v_mfma_f32_16x16x32_bf16 v[4:7], v[8:11], v[86:89], v[4:7]
	s_nop 0
	v_cvt_pk_bf16_f32 v68, v68, s0
	ds_write_b16 v161, v68
	v_cvt_pk_bf16_f32 v68, v69, s0
	v_cvt_pk_bf16_f32 v86, v44, v45
	v_cvt_pk_bf16_f32 v87, v46, v47
	v_cvt_pk_bf16_f32 v88, v20, v21
	v_cvt_pk_bf16_f32 v89, v22, v23
	ds_write_b16 v162, v68
	v_cvt_pk_bf16_f32 v68, v70, s0
	v_mfma_f32_16x16x32_bf16 v[8:11], v[8:11], v[86:89], v[82:85]
	ds_write_b16 v163, v68
	v_cvt_pk_bf16_f32 v68, v71, s0
	v_cvt_pk_bf16_f32 v4, v4, s0
	ds_write_b16 v164, v68
	ds_write_b16 v165, v4
	v_cvt_pk_bf16_f32 v4, v5, s0
	ds_write_b16 v166, v4
	v_cvt_pk_bf16_f32 v4, v6, s0
	ds_write_b16 v167, v4
	v_cvt_pk_bf16_f32 v4, v7, s0
	ds_write_b16 v168, v4
	v_cvt_pk_bf16_f32 v4, v8, s0
	ds_write_b16 v169, v4
	v_cvt_pk_bf16_f32 v4, v9, s0
	ds_write_b16 v170, v4
	v_cvt_pk_bf16_f32 v4, v10, s0
	ds_write_b16 v171, v4
	v_cvt_pk_bf16_f32 v4, v11, s0
	ds_write_b16 v172, v4
	ds_read2st64_b64 v[68:71], v173 offset0:17 offset1:18
	ds_read2st64_b64 v[82:85], v173 offset0:19 offset1:20
	ds_read_b128 v[90:93], v174 offset:20480
	ds_read_b128 v[236:239], v174 offset:20544
	v_mov_b32_e32 v88, v3
	s_waitcnt lgkmcnt(3)
	v_mov_b32_e32 v86, v68
	v_mov_b32_e32 v87, v69
	v_mov_b32_e32 v89, v3
	s_waitcnt lgkmcnt(1)
	v_pk_mul_f32 v[6:7], v[26:27], v[92:93]
	v_pk_mul_f32 v[4:5], v[24:25], v[90:91]
	v_pk_mul_f32 v[10:11], v[30:31], v[92:93]
	v_pk_mul_f32 v[8:9], v[28:29], v[90:91]
	v_pk_mul_f32 v[26:27], v[42:43], v[92:93]
	v_pk_mul_f32 v[24:25], v[40:41], v[90:91]
	v_mfma_f32_16x16x32_bf16 v[4:7], v[86:89], v[0:3], v[4:7]
	v_mov_b32_e32 v68, v82
	v_mov_b32_e32 v69, v83
	s_waitcnt lgkmcnt(0)
	v_pk_mul_f32 v[42:43], v[66:67], v[238:239]
	v_mfma_f32_16x16x32_bf16 v[8:11], v[86:89], v[72:75], v[8:11]
	v_mul_f32_e64 v40, v64, v236
	v_mul_f32_e64 v41, v65, v237
	v_pk_mul_f32 v[62:63], v[62:63], v[238:239]
	v_pk_mul_f32 v[60:61], v[60:61], v[236:237]
	v_mfma_f32_16x16x32_bf16 v[28:31], v[86:89], v[76:79], v[24:27]
	ds_read_b128 v[86:89], v174 offset:20608
	v_pk_mul_f32 v[58:59], v[58:59], v[238:239]
	v_pk_mul_f32 v[56:57], v[56:57], v[236:237]
	v_mov_b32_e32 v24, v70
	v_mov_b32_e32 v25, v71
	v_mov_b32_e32 v26, v3
	v_mov_b32_e32 v27, v3
	v_mov_b32_e32 v70, v3
	v_mov_b32_e32 v71, v3
	v_mfma_f32_16x16x32_bf16 v[40:43], v[24:27], v[0:3], v[40:43]
	v_mov_b32_e32 v82, 0
	v_mov_b32_e32 v83, 0
	v_mfma_f32_16x16x32_bf16 v[60:63], v[24:27], v[72:75], v[60:63]
	v_mfma_f32_16x16x32_bf16 v[64:67], v[24:27], v[76:79], v[56:59]
	ds_read_b128 v[24:27], v174 offset:20672
	s_waitcnt lgkmcnt(1)
	v_pk_mul_f32 v[46:47], v[46:47], v[88:89]
	v_pk_mul_f32 v[44:45], v[44:45], v[86:87]
	v_pk_mul_f32 v[54:55], v[54:55], v[88:89]
	v_pk_mul_f32 v[52:53], v[52:53], v[86:87]
	v_mfma_f32_16x16x32_bf16 v[56:59], v[68:71], v[76:79], v[44:47]
	v_mul_f32_e64 v50, v50, v88
	v_mul_f32_e64 v51, v51, v89
	v_pk_mul_f32 v[48:49], v[48:49], v[86:87]
	s_waitcnt lgkmcnt(0)
	v_pk_mul_f32 v[38:39], v[38:39], v[26:27]
	v_mov_b32_e32 v44, v84
	v_mov_b32_e32 v45, v85
	v_mov_b32_e32 v46, v3
	v_mov_b32_e32 v47, v3
	v_pk_mul_f32 v[36:37], v[36:37], v[24:25]
	v_pk_mul_f32 v[34:35], v[34:35], v[26:27]
	v_pk_mul_f32 v[32:33], v[32:33], v[24:25]
	v_pk_mul_f32 v[22:23], v[22:23], v[26:27]
	v_pk_mul_f32 v[20:21], v[20:21], v[24:25]
	v_mfma_f32_16x16x32_bf16 v[52:55], v[68:71], v[0:3], v[52:55]
	v_mfma_f32_16x16x32_bf16 v[48:51], v[68:71], v[72:75], v[48:51]
	v_mfma_f32_16x16x32_bf16 v[68:71], v[44:47], v[0:3], v[36:39]
	v_mfma_f32_16x16x32_bf16 v[72:75], v[44:47], v[72:75], v[32:35]
	v_mfma_f32_16x16x32_bf16 v[76:79], v[44:47], v[76:79], v[20:23]
	s_and_saveexec_b64 s[2:3], s[6:7]
	s_cbranch_execz .LBB0_590
	s_nop 0
	ds_read_b128 v[20:23], v160 offset:25344
	ds_read_b128 v[24:27], v160 offset:20992
	ds_read_b128 v[84:87], v160 offset:25408
	ds_read_b128 v[88:91], v160 offset:21056
	ds_read_b128 v[32:35], v160 offset:25472
	s_pack_ll_b32_b16 s20, 0, 0
	v_mov_b32_e32 v82, s20
	v_mov_b32_e32 v83, s20
	s_waitcnt lgkmcnt(3)
	v_mfma_f32_16x16x32_bf16 v[20:23], v[20:23], v[24:27], 0
	ds_read_b128 v[24:27], v160 offset:21120
	s_waitcnt lgkmcnt(2)
	v_mfma_f32_16x16x32_bf16 v[20:23], v[84:87], v[88:91], v[20:23]
	ds_read_b128 v[84:87], v160 offset:25536
	ds_read_b128 v[88:91], v160 offset:21184
	s_waitcnt lgkmcnt(2)
	v_mfma_f32_16x16x32_bf16 v[20:23], v[32:35], v[24:27], v[20:23]
	s_waitcnt lgkmcnt(0)
	v_mfma_f32_16x16x32_bf16 v[20:23], v[84:87], v[88:91], v[20:23]
	s_nop 7
	v_cndmask_b32_e64 v0, v20, 0, s[8:9]
	v_cndmask_b32_e64 v1, 0, v21, s[10:11]
	v_cvt_pk_bf16_f32 v80, v0, v1
	v_cndmask_b32_e64 v0, v22, 0, s[12:13]
	v_cndmask_b32_e64 v1, v23, 0, s[14:15]
	v_cvt_pk_bf16_f32 v81, v0, v1

; template <int MODE>
; __device__ void scan_unit(int swave, const Params& p, int j, int b, int h, int dir, char* shm) {
;     ...
;       const float KSC = 0.08838834764831845f;
;       const float qx0 = lo_bf(R.q), qx1 = hi_bf(R.q), qy0 = lo_bf(R.q2), qy1 = hi_bf(R.q2);
;       const float kx0 = lo_bf(R.k) * KSC, kx1 = hi_bf(R.k) * KSC, ky0 = lo_bf(R.k2) * KSC, ky1 = hi_bf(R.k2) * KSC;
;       const float c0 = R.cs.x, sn0 = R.cs.y, c1 = R.cs.z, sn1 = R.cs.w;
;       const float qa0 = qx0 * c0 - qy0 * sn0, qb0 = qx0 * sn0 + qy0 * c0, qa1 = qx1 * c1 - qy1 * sn1, qb1 = qx1 * sn1 + qy1 * c1;
;       const float ka0 = kx0 * c0 - ky0 * sn0, kb0 = kx0 * sn0 + ky0 * c0, ka1 = kx1 * c1 - ky1 * sn1, kb1 = kx1 * sn1 + ky1 * c1;
;       const float ein = ret_ein, eti = ret_eti, eout = ret_eout;
;       *(unsigned*)(qin + ti * QS + dp) = pk2(qa0 * ein, qa1 * ein); *(unsigned*)(qin + ti * QS + 64 + dp) = pk2(qb0 * ein, qb1 * ein);
;       *(unsigned*)(ktil + ti * QS + dp) = pk2(ka0 * eti, ka1 * eti); *(unsigned*)(ktil + ti * QS + 64 + dp) = pk2(kb0 * eti, kb1 * eti);
;       koutT[dp * 16 + ti] = f2bf(ka0 * eout); koutT[(dp + 1) * 16 + ti] = f2bf(ka1 * eout);
;       koutT[(64 + dp) * 16 + ti] = f2bf(kb0 * eout); koutT[(65 + dp) * 16 + ti] = f2bf(kb1 * eout);
;       if (ti == 0) { const float dd = ret_dd; *(float2*)(dec + dp) = make_float2(dd, dd); *(float2*)(dec + 64 + dp) = make_float2(dd, dd); }
;       const int c6 = vg * 6;
;       vT[(c6 + 0) * VS + ti] = (bf16_t)(R.v30 & 0xffff); vT[(c6 + 1) * VS + ti] = (bf16_t)(R.v30 >> 16);
;       vT[(c6 + 2) * VS + ti] = (bf16_t)(R.v31 & 0xffff); vT[(c6 + 3) * VS + ti] = (bf16_t)(R.v31 >> 16);
;       vT[(c6 + 4) * VS + ti] = (bf16_t)(R.v32 & 0xffff); vT[(c6 + 5) * VS + ti] = (bf16_t)(R.v32 >> 16);
;     }
;   };
;   f32x4 S[4][NVT];
; #pragma unroll
;   for (int a = 0; a < 4; ++a)
; #pragma unroll
;     for (int t = 0; t < NVT; ++t) S[a][t] = (f32x4){0.f, 0.f, 0.f, 0.f};
;   auto compute = [&](const char* buf, bf16_t* obuf) {
;     const bf16_t* qin = (const bf16_t*)buf; const bf16_t* ktil = (const bf16_t*)(buf + OFF_KT); const bf16_t* koutT = (const bf16_t*)(buf + OFF_KO);
;     const bf16_t* vT = (const bf16_t*)(buf + OFF_VT); const float* dec = (const float*)(buf + OFF_DEC);
;     bf16x8 Asc = {0, 0, 0, 0, 0, 0, 0, 0};
;     if (KS == 1 || wk == 0) {
;       f32x4 sc = {0.f, 0.f, 0.f, 0.f};
; #pragma unroll
.LBB0_601:
	s_or_b64 exec, exec, s[2:3]
	v_lshlrev_b32_e32 v68, 16, v106
	v_and_b32_e32 v69, 0xffff0000, v106
	v_mov_b32_e32 v75, v18
	v_mov_b32_e32 v18, v17
	v_lshlrev_b32_e32 v0, 16, v107
	v_and_b32_e32 v1, 0xffff0000, v107
	v_mov_b32_e32 v74, v16
	v_pk_mul_f32 v[16:17], v[18:19], v[68:69]
	v_lshlrev_b32_e32 v72, 16, v104
	v_pk_fma_f32 v[16:17], v[74:75], v[0:1], v[16:17] neg_lo:[0,0,1] neg_hi:[0,0,1]
	v_pk_mul_f32 v[0:1], v[18:19], v[0:1]
	v_and_b32_e32 v73, 0xffff0000, v104
	v_pk_fma_f32 v[0:1], v[74:75], v[68:69], v[0:1]
	v_pk_mul_f32 v[16:17], v[124:125], v[16:17]
	v_pk_mul_f32 v[0:1], v[124:125], v[0:1]
	s_mov_b32 s2, 0x3db504f3
	v_lshlrev_b32_e32 v70, 16, v105
	v_and_b32_e32 v71, 0xffff0000, v105
	v_cvt_pk_bf16_f32 v2, v16, v17
	v_cvt_pk_bf16_f32 v0, v0, v1
	v_pk_mul_f32 v[16:17], v[72:73], s[2:3] op_sel_hi:[1,0]
	ds_write2_b32 v121, v2, v0 offset1:32
	v_pk_mul_f32 v[0:1], v[70:71], s[2:3] op_sel_hi:[1,0]
	v_pk_mul_f32 v[68:69], v[18:19], v[16:17]
	s_nop 0
	v_pk_fma_f32 v[68:69], v[74:75], v[0:1], v[68:69] neg_lo:[0,0,1] neg_hi:[0,0,1]
	v_pk_mul_f32 v[0:1], v[0:1], v[18:19]
	v_pk_mul_f32 v[70:71], v[126:127], v[68:69]
	v_pk_fma_f32 v[0:1], v[16:17], v[74:75], v[0:1]
	v_cvt_pk_bf16_f32 v2, v70, v71
	v_pk_mul_f32 v[16:17], v[126:127], v[0:1]
	v_mul_f32_e32 v0, v117, v0
	v_cvt_pk_bf16_f32 v16, v16, v17
	ds_write2_b32 v135, v2, v16 offset0:64 offset1:96
	v_mul_f32_e32 v2, v117, v68
	v_cvt_pk_bf16_f32 v2, v2, s0
	v_cvt_pk_bf16_f32 v0, v0, s0
	ds_write_b16 v136, v2 offset:8704
	v_mul_f32_e32 v2, v117, v69
	ds_write_b16 v136, v0 offset:10752
	v_mul_f32_e32 v0, v117, v1
	v_cvt_pk_bf16_f32 v2, v2, s0
	v_cvt_pk_bf16_f32 v0, v0, s0
	ds_write_b16 v136, v2 offset:8736
	ds_write_b16 v136, v0 offset:10784
	s_and_saveexec_b64 s[2:3], s[16:17]
	v_add_u32_e32 v0, 0x5000, v141
	ds_write2_b64 v0, v[128:129], v[128:129] offset1:32
	s_or_b64 exec, exec, s[2:3]
	v_lshlrev_b32_e32 v16, 16, v102
	v_and_b32_e32 v17, 0xffff0000, v102
	v_mov_b32_e32 v71, v14
	v_mov_b32_e32 v14, v13
	v_lshlrev_b32_e32 v0, 16, v103
	v_and_b32_e32 v1, 0xffff0000, v103
	v_mov_b32_e32 v70, v12
	v_pk_mul_f32 v[12:13], v[14:15], v[16:17]
	v_lshlrev_b32_e32 v68, 16, v97
	v_pk_fma_f32 v[12:13], v[70:71], v[0:1], v[12:13] neg_lo:[0,0,1] neg_hi:[0,0,1]
	v_pk_mul_f32 v[0:1], v[14:15], v[0:1]
	v_and_b32_e32 v69, 0xffff0000, v97
	v_pk_fma_f32 v[0:1], v[70:71], v[16:17], v[0:1]
	v_pk_mul_f32 v[12:13], v[124:125], v[12:13]
	v_pk_mul_f32 v[0:1], v[124:125], v[0:1]
	s_mov_b32 s2, 0x3db504f3
	v_lshlrev_b32_e32 v18, 16, v101
	v_and_b32_e32 v19, 0xffff0000, v101
	v_cvt_pk_bf16_f32 v2, v12, v13
	v_cvt_pk_bf16_f32 v0, v0, v1
	v_pk_mul_f32 v[12:13], v[68:69], s[2:3] op_sel_hi:[1,0]
	ds_write_b16 v137, v98 offset:12800
	ds_write_b16_d16_hi v137, v98 offset:12840
	ds_write_b16 v137, v99 offset:12880
	ds_write_b16_d16_hi v137, v99 offset:12920
	ds_write_b16 v137, v100 offset:12960
	ds_write_b16_d16_hi v137, v100 offset:13000
	ds_write2_b32 v139, v2, v0 offset0:128 offset1:160
	v_pk_mul_f32 v[0:1], v[18:19], s[2:3] op_sel_hi:[1,0]
	v_pk_mul_f32 v[16:17], v[14:15], v[12:13]
	s_nop 0
	v_pk_fma_f32 v[16:17], v[70:71], v[0:1], v[16:17] neg_lo:[0,0,1] neg_hi:[0,0,1]
	v_pk_mul_f32 v[0:1], v[0:1], v[14:15]
	v_pk_mul_f32 v[18:19], v[126:127], v[16:17]
	v_pk_fma_f32 v[0:1], v[12:13], v[70:71], v[0:1]
	v_cvt_pk_bf16_f32 v2, v18, v19
	v_pk_mul_f32 v[12:13], v[126:127], v[0:1]
	v_mul_f32_e32 v0, v117, v0
	v_cvt_pk_bf16_f32 v12, v12, v13
	ds_write2_b32 v140, v2, v12 offset0:192 offset1:224
	v_mul_f32_e32 v2, v117, v16
	v_cvt_pk_bf16_f32 v2, v2, s0
	v_cvt_pk_bf16_f32 v0, v0, s0
	ds_write_b16 v136, v2 offset:29696
	v_mul_f32_e32 v2, v117, v17
	ds_write_b16 v136, v0 offset:31744
	v_mul_f32_e32 v0, v117, v1
	v_cvt_pk_bf16_f32 v2, v2, s0
	v_cvt_pk_bf16_f32 v0, v0, s0
	ds_write_b16 v136, v2 offset:29728
	ds_write_b16 v136, v0 offset:31776
	s_and_saveexec_b64 s[2:3], s[16:17]
	v_add_u32_e32 v0, 0xa000, v141
	ds_write2_b64 v0, v[128:129], v[128:129] offset0:64 offset1:96
	s_or_b64 exec, exec, s[2:3]
	v_mov_b32_e32 v12, 0
	v_mov_b32_e32 v68, 0
	v_mov_b32_e32 v69, 0
	v_mov_b32_e32 v70, 0
	v_mov_b32_e32 v71, 0
	ds_write_b16 v137, v94 offset:33792
	ds_write_b16_d16_hi v137, v94 offset:33832
	ds_write_b16 v137, v95 offset:33872
	ds_write_b16_d16_hi v137, v95 offset:33912
	ds_write_b16 v137, v96 offset:33952
	ds_write_b16_d16_hi v137, v96 offset:33992
	s_and_saveexec_b64 s[2:3], s[6:7]
	s_cbranch_execz .LBB0_607
	ds_read_b128 v[14:17], v160 offset:46336
	ds_read_b128 v[68:71], v160 offset:41984
	ds_read_b128 v[76:79], v160 offset:46400
	ds_read_b128 v[80:83], v160 offset:42048
	ds_read_b128 v[72:75], v160 offset:46464
	s_pack_ll_b32_b16 s20, 0, 0
	s_waitcnt lgkmcnt(3)
	v_mfma_f32_16x16x32_bf16 v[14:17], v[14:17], v[68:71], 0
	ds_read_b128 v[68:71], v160 offset:42112
	s_waitcnt lgkmcnt(2)
	v_mfma_f32_16x16x32_bf16 v[14:17], v[76:79], v[80:83], v[14:17]
	ds_read_b128 v[76:79], v160 offset:46528
	ds_read_b128 v[80:83], v160 offset:42176
	s_waitcnt lgkmcnt(2)
	v_mfma_f32_16x16x32_bf16 v[14:17], v[72:75], v[68:71], v[14:17]
	s_waitcnt lgkmcnt(0)
	v_mfma_f32_16x16x32_bf16 v[14:17], v[76:79], v[80:83], v[14:17]
	v_mov_b32_e32 v70, s20
	v_mov_b32_e32 v71, s20
	s_nop 5
	v_cndmask_b32_e64 v0, v14, 0, s[8:9]
	v_cndmask_b32_e64 v1, 0, v15, s[10:11]
	v_cvt_pk_bf16_f32 v68, v0, v1
	v_cndmask_b32_e64 v0, v16, 0, s[12:13]
	v_cndmask_b32_e64 v1, v17, 0, s[14:15]
	v_cvt_pk_bf16_f32 v69, v0, v1

; __device__ __forceinline__ bf16_t f2bf(float f) { return (bf16_t)(pk2(f, 0.f) & 0xffffu); }
; template <int MODE>
; __device__ void scan_unit(int swave, const Params& p, int j, int b, int h, int dir, char* shm) {
;     ...
;     if (KS == 1 || wk == 0) {
;       f32x4 sc = {0.f, 0.f, 0.f, 0.f};
; #pragma unroll
;       for (int m = 0; m < DK / 32; ++m) {
;         const bf16x8 a = *(const bf16x8*)(ktil + r * QS + m * 32 + q4 * 8);
;         const bf16x8 bb = *(const bf16x8*)(qin + r * QS + m * 32 + q4 * 8);
;         sc = __builtin_amdgcn_mfma_f32_16x16x32_bf16(a, bb, sc, 0, 0, 0);
;       }
;       {
;     ...
;     for (int m = 0; m < 2; ++m) {
;       const uint2 lo = *(const uint2*)(qin + r * QS + slab + (2 * m) * 16 + q4 * 4);
;       const uint2 hi = *(const uint2*)(qin + r * QS + slab + (2 * m + 1) * 16 + q4 * 4);
;       Aq[m] = (bf16x8){(short)(lo.x & 0xffff), (short)(lo.x >> 16), (short)(lo.y & 0xffff), (short)(lo.y >> 16),
;                        (short)(hi.x & 0xffff), (short)(hi.x >> 16), (short)(hi.y & 0xffff), (short)(hi.y >> 16)};
;     }
;     f32x4 o[NVT];
; #pragma unroll
;     for (int t = 0; t < NVT; ++t) {
;       o[t] = (f32x4){0.f, 0.f, 0.f, 0.f};
;       if (KS == 1 || wk == 0) o[t] = __builtin_amdgcn_mfma_f32_16x16x32_bf16(Asc, Bv[t], o[t], 0, 0, 0);
;     }
; #pragma unroll
;     for (int m = 0; m < 2; ++m)
; #pragma unroll
;       for (int t = 0; t < NVT; ++t) {
;         const f32x4 s0 = S[2 * m][t], s1 = S[2 * m + 1][t];
;         union { unsigned u[4]; bf16x8 v; } cv;
;         cv.u[0] = pk2(s0[0], s0[1]); cv.u[1] = pk2(s0[2], s0[3]); cv.u[2] = pk2(s1[0], s1[1]); cv.u[3] = pk2(s1[2], s1[3]);
;         o[t] = __builtin_amdgcn_mfma_f32_16x16x32_bf16(Aq[m], cv.v, o[t], 0, 0, 0);
;       }
; #pragma unroll
;     for (int t = 0; t < NVT; ++t)
; #pragma unroll
;       for (int jj = 0; jj < 4; ++jj) obuf[(wk * 16 + q4 * 4 + jj) * OS + (vt0 + t) * 16 + r] = f2bf(o[t][jj]);
; #pragma unroll
;     for (int kt = 0; kt < 4; ++kt) {
;       const uint2 kk = *(const uint2*)(koutT + (slab + kt * 16 + r) * 16 + q4 * 4);
;       const bf16x8 Ak = {(short)(kk.x & 0xffff), (short)(kk.x >> 16), (short)(kk.y & 0xffff), (short)(kk.y >> 16), 0, 0, 0, 0};
;       const f32x4 dc = *(const f32x4*)(dec + slab + kt * 16 + q4 * 4);
; #pragma unroll
;       for (int t = 0; t < NVT; ++t) S[kt][t] = __builtin_amdgcn_mfma_f32_16x16x32_bf16(Ak, Bv[t], S[kt][t] * dc, 0, 0, 0);
.LBB0_613:
	s_or_b64 exec, exec, s[2:3]
	s_waitcnt lgkmcnt(1)
	v_bfi_b32 v82, s30, v82, v82
	s_waitcnt lgkmcnt(0)
	v_bfi_b32 v18, s30, v18, v18
	v_cvt_pk_bf16_f32 v68, v20, v21
	v_cvt_pk_bf16_f32 v69, v22, v23
	v_cvt_pk_bf16_f32 v70, v32, v33
	v_cvt_pk_bf16_f32 v71, v34, v35
	v_mov_b32_e32 v85, 0
	s_nop 0
	v_mfma_f32_16x16x32_bf16 v[68:71], v[80:83], v[68:71], v[86:89]
	s_nop 2
	v_cvt_pk_bf16_f32 v86, v24, v25
	v_cvt_pk_bf16_f32 v87, v26, v27
	v_cvt_pk_bf16_f32 v88, v36, v37
	v_cvt_pk_bf16_f32 v89, v38, v39
	s_nop 1
	v_mfma_f32_16x16x32_bf16 v[12:15], v[80:83], v[86:89], v[12:15]
	v_cvt_pk_bf16_f32 v86, v28, v29
	v_cvt_pk_bf16_f32 v87, v30, v31
	v_cvt_pk_bf16_f32 v88, v64, v65
	v_cvt_pk_bf16_f32 v89, v66, v67
	s_nop 1
	v_mfma_f32_16x16x32_bf16 v[80:83], v[80:83], v[86:89], v[90:93]
	v_cvt_pk_bf16_f32 v86, v40, v41
	v_cvt_pk_bf16_f32 v87, v42, v43
	v_cvt_pk_bf16_f32 v88, v52, v53
	v_cvt_pk_bf16_f32 v89, v54, v55
	s_nop 1
	v_mfma_f32_16x16x32_bf16 v[68:71], v[16:19], v[86:89], v[68:71]
	v_cvt_pk_bf16_f32 v86, v44, v45
	v_cvt_pk_bf16_f32 v87, v46, v47
	v_cvt_pk_bf16_f32 v88, v56, v57
	v_cvt_pk_bf16_f32 v89, v58, v59
	s_nop 1
	v_mfma_f32_16x16x32_bf16 v[12:15], v[16:19], v[86:89], v[12:15]
	s_nop 0
	v_cvt_pk_bf16_f32 v68, v68, s0
	ds_write_b16 v191, v68
	v_cvt_pk_bf16_f32 v68, v69, s0
	v_cvt_pk_bf16_f32 v86, v48, v49
	v_cvt_pk_bf16_f32 v87, v50, v51
	v_cvt_pk_bf16_f32 v88, v60, v61
	v_cvt_pk_bf16_f32 v89, v62, v63
	ds_write_b16 v192, v68
	v_cvt_pk_bf16_f32 v68, v70, s0
	v_mfma_f32_16x16x32_bf16 v[16:19], v[16:19], v[86:89], v[80:83]
	ds_write_b16 v193, v68
	v_cvt_pk_bf16_f32 v68, v71, s0
	v_cvt_pk_bf16_f32 v12, v12, s0
	ds_write_b16 v194, v68
	ds_write_b16 v195, v12
	v_cvt_pk_bf16_f32 v12, v13, s0
	ds_write_b16 v196, v12
	v_cvt_pk_bf16_f32 v12, v14, s0
	ds_write_b16 v197, v12
	v_cvt_pk_bf16_f32 v12, v15, s0
	ds_write_b16 v198, v12
	v_cvt_pk_bf16_f32 v12, v16, s0
	ds_write_b16 v199, v12
	v_cvt_pk_bf16_f32 v12, v17, s0
	ds_write_b16 v200, v12
	v_cvt_pk_bf16_f32 v12, v18, s0
	ds_write_b16 v201, v12
	v_cvt_pk_bf16_f32 v12, v19, s0
	ds_write_b16 v202, v12
	ds_read2st64_b64 v[12:15], v173 offset0:99 offset1:100
	ds_read2st64_b64 v[80:83], v173 offset0:101 offset1:102
	ds_read_b128 v[68:71], v190 offset:62464
	ds_read_b128 v[100:103], v190 offset:62528
	v_mov_b32_e32 v18, v3
	s_waitcnt lgkmcnt(3)
	v_mov_b32_e32 v16, v12
	v_mov_b32_e32 v17, v13
	v_mov_b32_e32 v19, v3
	s_waitcnt lgkmcnt(1)
	v_pk_mul_f32 v[22:23], v[22:23], v[70:71]
	v_pk_mul_f32 v[20:21], v[20:21], v[68:69]
	s_waitcnt lgkmcnt(0)
	v_pk_mul_f32 v[12:13], v[32:33], v[100:101]
	v_mov_b32_e32 v86, 0
	v_mfma_f32_16x16x32_bf16 v[96:99], v[16:19], v[0:3], v[20:23]
	v_mov_b32_e32 v87, 0
	s_nop 1
	v_pk_mul_f32 v[22:23], v[26:27], v[70:71]
	v_pk_mul_f32 v[20:21], v[24:25], v[68:69]
	v_pk_mul_f32 v[26:27], v[66:67], v[102:103]
	v_pk_mul_f32 v[24:25], v[64:65], v[100:101]
	v_mfma_f32_16x16x32_bf16 v[92:95], v[16:19], v[76:79], v[20:23]
	s_nop 2
	v_mul_f32_e64 v22, v30, v70
	v_mul_f32_e64 v23, v31, v71
	v_pk_mul_f32 v[20:21], v[28:29], v[68:69]
	v_mov_b32_e32 v28, v80
	v_mov_b32_e32 v29, v81
	v_mfma_f32_16x16x32_bf16 v[88:91], v[16:19], v[72:75], v[20:23]
	v_mov_b32_e32 v16, v14
	v_mov_b32_e32 v17, v15
	v_pk_mul_f32 v[14:15], v[34:35], v[102:103]
	v_mov_b32_e32 v30, v3
	v_mov_b32_e32 v31, v3
	v_mfma_f32_16x16x32_bf16 v[20:23], v[16:19], v[0:3], v[12:15]
	s_nop 2
	v_mul_f32_e64 v14, v38, v102
	v_mul_f32_e64 v15, v39, v103
	v_pk_mul_f32 v[12:13], v[36:37], v[100:101]
	ds_read_b128 v[36:39], v190 offset:62592
	s_nop 0
	v_mfma_f32_16x16x32_bf16 v[12:15], v[16:19], v[76:79], v[12:15]
	v_mfma_f32_16x16x32_bf16 v[16:19], v[16:19], v[72:75], v[24:27]
	s_nop 2
	ds_read_b128 v[24:27], v190 offset:62656
	s_waitcnt lgkmcnt(1)
	v_pk_mul_f32 v[34:35], v[42:43], v[38:39]
	v_pk_mul_f32 v[32:33], v[40:41], v[36:37]
	s_waitcnt lgkmcnt(0)
	v_pk_mul_f32 v[42:43], v[54:55], v[26:27]
	v_mfma_f32_16x16x32_bf16 v[68:71], v[28:31], v[0:3], v[32:35]
	v_mul_f32_e64 v40, v52, v24
	v_mul_f32_e64 v41, v53, v25
	s_nop 0
	v_pk_mul_f32 v[34:35], v[46:47], v[38:39]
	v_pk_mul_f32 v[32:33], v[44:45], v[36:37]
	v_pk_mul_f32 v[38:39], v[50:51], v[38:39]
	v_pk_mul_f32 v[36:37], v[48:49], v[36:37]
	v_mfma_f32_16x16x32_bf16 v[32:35], v[28:31], v[76:79], v[32:35]
	s_nop 0
	v_mfma_f32_16x16x32_bf16 v[36:39], v[28:31], v[72:75], v[36:39]
	v_mov_b32_e32 v28, v82
	v_mov_b32_e32 v29, v83
	s_nop 1
	v_mfma_f32_16x16x32_bf16 v[80:83], v[28:31], v[0:3], v[40:43]
	s_nop 2
	v_mul_f32_e64 v42, v58, v26
	v_mul_f32_e64 v43, v59, v27
	v_pk_mul_f32 v[40:41], v[56:57], v[24:25]
	v_pk_mul_f32 v[26:27], v[62:63], v[26:27]
	v_pk_mul_f32 v[24:25], v[60:61], v[24:25]
	v_mfma_f32_16x16x32_bf16 v[76:79], v[28:31], v[76:79], v[40:43]
	s_nop 0
	v_mfma_f32_16x16x32_bf16 v[72:75], v[28:31], v[72:75], v[24:27]
	s_and_saveexec_b64 s[2:3], s[6:7]
	s_cbranch_execz .LBB0_615
	s_nop 0
	ds_read_b128 v[24:27], v203
	ds_read_b128 v[28:31], v160 offset:62976
	ds_read_b128 v[100:103], v203 offset:64
	ds_read_b128 v[104:107], v160 offset:63040
	ds_read_b128 v[40:43], v203 offset:128
	s_pack_ll_b32_b16 s20, 0, 0
	v_mov_b32_e32 v86, s20
	v_mov_b32_e32 v87, s20
	s_waitcnt lgkmcnt(3)
	v_mfma_f32_16x16x32_bf16 v[24:27], v[24:27], v[28:31], 0
	ds_read_b128 v[28:31], v160 offset:63104
	s_waitcnt lgkmcnt(2)
	v_mfma_f32_16x16x32_bf16 v[24:27], v[100:103], v[104:107], v[24:27]
	ds_read_b128 v[100:103], v203 offset:192
	ds_read_b128 v[104:107], v160 offset:63168
	s_waitcnt lgkmcnt(2)
	v_mfma_f32_16x16x32_bf16 v[24:27], v[40:43], v[28:31], v[24:27]
	s_waitcnt lgkmcnt(0)
	v_mfma_f32_16x16x32_bf16 v[24:27], v[100:103], v[104:107], v[24:27]
	s_nop 7
	v_cndmask_b32_e64 v0, v24, 0, s[8:9]
	v_cndmask_b32_e64 v1, 0, v25, s[10:11]
	v_cvt_pk_bf16_f32 v84, v0, v1
	v_cndmask_b32_e64 v0, v26, 0, s[12:13]
	v_cndmask_b32_e64 v1, v27, 0, s[14:15]
	v_cvt_pk_bf16_f32 v85, v0, v1
